# removed the per-block s_setprio 1/0 pairs around the merged 32-MFMA GEMM blocks (timing-only change)
# baseline (speedup 1.0000x reference)
.LBB0_388:
	s_cmpk_eq_i32 s85, 0xf80
	s_cselect_b32 s39, s5, s15
	s_cselect_b32 s38, s4, s14
	s_cselect_b32 s88, s7, s13
	s_cselect_b32 s89, s6, s12
	s_add_i32 s36, s86, 3
	s_cmpk_eq_i32 s85, 0xf80
	s_cselect_b32 s36, 1, s36
	s_add_i32 s87, s86, 2
	s_cmpk_eq_i32 s85, 0xf80
	s_cselect_b32 s37, 0, s87
	s_add_i32 s37, s37, s64
	s_add_i32 s36, s36, s64
	s_add_i32 s40, s66, s85
	s_lshl_b32 s37, s37, 7
	s_lshl_b32 s36, s36, 7
	s_and_b32 s91, s40, 0xf80
	s_and_b32 s92, s37, 0xf80
	s_and_b32 s90, s36, 0xf80
	s_add_u32 s40, s89, s92
	s_addc_u32 s41, s88, 0
	s_add_u32 s38, s38, s92
	s_addc_u32 s39, s39, 0
	s_add_u32 s36, s12, s91
	s_addc_u32 s37, s13, 0
	s_add_u32 s36, s36, 0x84000
	s_addc_u32 s37, s37, 0
	s_add_u32 s92, s14, s91
	s_addc_u32 s93, s15, 0
	v_add_u32_e32 v137, 0x10000, v146
	ds_read_b128 v[160:163], v137
	ds_read_b128 v[164:167], v137 offset:1024
	ds_read_b128 v[168:171], v137 offset:2048
	ds_read_b128 v[188:191], v137 offset:3072
	v_add_u32_e32 v144, 0x14000, v146
	ds_read_b128 v[224:227], v144
	ds_read_b128 v[228:231], v144 offset:1024
	ds_read_b128 v[232:235], v144 offset:2048
	ds_read_b128 v[236:239], v144 offset:3072
	ds_read_b128 v[192:195], v139
	ds_read_b128 v[196:199], v139 offset:1024
	ds_read_b128 v[200:203], v139 offset:2048
	ds_read_b128 v[204:207], v139 offset:3072
	v_lshl_add_u64 v[172:173], s[92:93], 0, v[134:135]
	s_mov_b32 m0, s76
	s_nop 0
	global_load_lds_dwordx4 v[172:173], off
	v_lshl_add_u64 v[172:173], s[92:93], 0, v[130:131]
	s_mov_b32 m0, s77
	s_nop 0
	global_load_lds_dwordx4 v[172:173], off
	v_lshl_add_u64 v[172:173], s[36:37], 0, v[132:133]
	s_mov_b32 m0, s78
	s_nop 0
	global_load_lds_dwordx4 v[172:173], off
	v_lshl_add_u64 v[172:173], s[36:37], 0, v[128:129]
	s_mov_b32 m0, s79
	s_nop 0
	global_load_lds_dwordx4 v[172:173], off
	s_waitcnt lgkmcnt(11)
	ds_read_b128 v[208:211], v139 offset:4096
	ds_read_b128 v[212:215], v139 offset:5120
	ds_read_b128 v[216:219], v139 offset:6144
	ds_read_b128 v[220:223], v139 offset:7168
	s_waitcnt vmcnt(6)
	s_waitcnt lgkmcnt(8)
	s_barrier
	s_waitcnt lgkmcnt(0)
	v_mfma_f32_16x16x32_bf16 v[124:127], v[160:163], v[192:195], v[124:127]
	v_mfma_f32_16x16x32_bf16 v[120:123], v[168:171], v[192:195], v[120:123]
	v_mfma_f32_16x16x32_bf16 v[112:115], v[160:163], v[200:203], v[112:115]
	v_mfma_f32_16x16x32_bf16 v[108:111], v[168:171], v[200:203], v[108:111]
	v_mfma_f32_16x16x32_bf16 v[104:107], v[160:163], v[208:211], v[104:107]
	v_mfma_f32_16x16x32_bf16 v[96:99], v[168:171], v[208:211], v[96:99]
	v_mfma_f32_16x16x32_bf16 v[88:91], v[160:163], v[216:219], v[88:91]
	v_mfma_f32_16x16x32_bf16 v[80:83], v[168:171], v[216:219], v[80:83]
	v_mfma_f32_16x16x32_bf16 v[124:127], v[164:167], v[196:199], v[124:127]
	v_mfma_f32_16x16x32_bf16 v[120:123], v[188:191], v[196:199], v[120:123]
	v_mfma_f32_16x16x32_bf16 v[112:115], v[164:167], v[204:207], v[112:115]
	v_mfma_f32_16x16x32_bf16 v[108:111], v[188:191], v[204:207], v[108:111]
	v_mfma_f32_16x16x32_bf16 v[104:107], v[164:167], v[212:215], v[104:107]
	v_mfma_f32_16x16x32_bf16 v[96:99], v[188:191], v[212:215], v[96:99]
	v_mfma_f32_16x16x32_bf16 v[88:91], v[164:167], v[220:223], v[88:91]
	v_mfma_f32_16x16x32_bf16 v[80:83], v[188:191], v[220:223], v[80:83]
	v_mfma_f32_16x16x32_bf16 v[116:119], v[224:227], v[192:195], v[116:119]
	v_mfma_f32_16x16x32_bf16 v[100:103], v[232:235], v[192:195], v[100:103]
	v_mfma_f32_16x16x32_bf16 v[92:95], v[224:227], v[200:203], v[92:95]
	v_mfma_f32_16x16x32_bf16 v[84:87], v[232:235], v[200:203], v[84:87]
	v_mfma_f32_16x16x32_bf16 v[76:79], v[224:227], v[208:211], v[76:79]
	v_mfma_f32_16x16x32_bf16 v[72:75], v[232:235], v[208:211], v[72:75]
	v_mfma_f32_16x16x32_bf16 v[68:71], v[224:227], v[216:219], v[68:71]
	v_mfma_f32_16x16x32_bf16 v[64:67], v[232:235], v[216:219], v[64:67]
	v_mfma_f32_16x16x32_bf16 v[116:119], v[228:231], v[196:199], v[116:119]
	v_mfma_f32_16x16x32_bf16 v[100:103], v[236:239], v[196:199], v[100:103]
	v_mfma_f32_16x16x32_bf16 v[92:95], v[228:231], v[204:207], v[92:95]
	v_mfma_f32_16x16x32_bf16 v[84:87], v[236:239], v[204:207], v[84:87]
	v_mfma_f32_16x16x32_bf16 v[76:79], v[228:231], v[212:215], v[76:79]
	v_mfma_f32_16x16x32_bf16 v[72:75], v[236:239], v[212:215], v[72:75]
	v_mfma_f32_16x16x32_bf16 v[68:71], v[228:231], v[220:223], v[68:71]
	v_mfma_f32_16x16x32_bf16 v[64:67], v[236:239], v[220:223], v[64:67]
	s_barrier
	ds_read_b128 v[192:195], v139 offset:16384
	ds_read_b128 v[196:199], v139 offset:17408
	ds_read_b128 v[200:203], v139 offset:18432
	ds_read_b128 v[204:207], v139 offset:19456
	ds_read_b128 v[208:211], v139 offset:20480
	ds_read_b128 v[212:215], v139 offset:21504
	ds_read_b128 v[216:219], v139 offset:22528
	ds_read_b128 v[220:223], v139 offset:23552
	s_add_u32 s92, s92, 0x84000
	s_addc_u32 s93, s93, 0
	v_lshl_add_u64 v[172:173], s[92:93], 0, v[134:135]
	s_mov_b32 m0, s81
	s_nop 0
	global_load_lds_dwordx4 v[172:173], off
	v_lshl_add_u64 v[172:173], s[92:93], 0, v[130:131]
	s_mov_b32 m0, s82
	s_nop 0
	global_load_lds_dwordx4 v[172:173], off
	v_lshl_add_u64 v[172:173], s[40:41], 0, v[132:133]
	s_mov_b32 m0, s52
	s_nop 0
	global_load_lds_dwordx4 v[172:173], off
	v_lshl_add_u64 v[172:173], s[40:41], 0, v[128:129]
	s_mov_b32 m0, s53
	s_nop 0
	global_load_lds_dwordx4 v[172:173], off
	s_waitcnt vmcnt(4)
	s_barrier
	s_waitcnt lgkmcnt(0)
	v_mfma_f32_16x16x32_bf16 v[60:63], v[160:163], v[192:195], v[60:63]
	v_mfma_f32_16x16x32_bf16 v[56:59], v[168:171], v[192:195], v[56:59]
	v_mfma_f32_16x16x32_bf16 v[52:55], v[160:163], v[200:203], v[52:55]
	v_mfma_f32_16x16x32_bf16 v[48:51], v[168:171], v[200:203], v[48:51]
	v_mfma_f32_16x16x32_bf16 v[40:43], v[160:163], v[208:211], v[40:43]
	v_mfma_f32_16x16x32_bf16 v[36:39], v[168:171], v[208:211], v[36:39]
	v_mfma_f32_16x16x32_bf16 v[24:27], v[160:163], v[216:219], v[24:27]
	v_mfma_f32_16x16x32_bf16 v[20:23], v[168:171], v[216:219], v[20:23]
	v_mfma_f32_16x16x32_bf16 v[60:63], v[164:167], v[196:199], v[60:63]
	v_mfma_f32_16x16x32_bf16 v[56:59], v[188:191], v[196:199], v[56:59]
	v_mfma_f32_16x16x32_bf16 v[52:55], v[164:167], v[204:207], v[52:55]
	v_mfma_f32_16x16x32_bf16 v[48:51], v[188:191], v[204:207], v[48:51]
	v_mfma_f32_16x16x32_bf16 v[40:43], v[164:167], v[212:215], v[40:43]
	v_mfma_f32_16x16x32_bf16 v[36:39], v[188:191], v[212:215], v[36:39]
	v_mfma_f32_16x16x32_bf16 v[24:27], v[164:167], v[220:223], v[24:27]
	v_mfma_f32_16x16x32_bf16 v[20:23], v[188:191], v[220:223], v[20:23]
	v_mfma_f32_16x16x32_bf16 v[44:47], v[224:227], v[192:195], v[44:47]
	v_mfma_f32_16x16x32_bf16 v[32:35], v[232:235], v[192:195], v[32:35]
	v_mfma_f32_16x16x32_bf16 v[28:31], v[224:227], v[200:203], v[28:31]
	v_mfma_f32_16x16x32_bf16 v[16:19], v[232:235], v[200:203], v[16:19]
	v_mfma_f32_16x16x32_bf16 v[12:15], v[224:227], v[208:211], v[12:15]
	v_mfma_f32_16x16x32_bf16 v[8:11], v[232:235], v[208:211], v[8:11]
	v_mfma_f32_16x16x32_bf16 v[4:7], v[224:227], v[216:219], v[4:7]
	v_mfma_f32_16x16x32_bf16 v[0:3], v[232:235], v[216:219], v[0:3]
	v_mfma_f32_16x16x32_bf16 v[44:47], v[228:231], v[196:199], v[44:47]
	v_mfma_f32_16x16x32_bf16 v[32:35], v[236:239], v[196:199], v[32:35]
	v_mfma_f32_16x16x32_bf16 v[28:31], v[228:231], v[204:207], v[28:31]
	v_mfma_f32_16x16x32_bf16 v[16:19], v[236:239], v[204:207], v[16:19]
	v_mfma_f32_16x16x32_bf16 v[12:15], v[228:231], v[212:215], v[12:15]
	v_mfma_f32_16x16x32_bf16 v[8:11], v[236:239], v[212:215], v[8:11]
	v_mfma_f32_16x16x32_bf16 v[4:7], v[228:231], v[220:223], v[4:7]
	v_mfma_f32_16x16x32_bf16 v[0:3], v[236:239], v[220:223], v[0:3]
	s_barrier
	v_add_u32_e32 v137, 0x18000, v146
	ds_read_b128 v[160:163], v137
	ds_read_b128 v[164:167], v137 offset:1024
	ds_read_b128 v[168:171], v137 offset:2048
	ds_read_b128 v[188:191], v137 offset:3072
	v_add_u32_e32 v144, 0x1c000, v146
	ds_read_b128 v[224:227], v144
	ds_read_b128 v[228:231], v144 offset:1024
	ds_read_b128 v[232:235], v144 offset:2048
	ds_read_b128 v[236:239], v144 offset:3072
	ds_read_b128 v[192:195], v139 offset:32768
	ds_read_b128 v[196:199], v139 offset:33792
	ds_read_b128 v[200:203], v139 offset:34816
	ds_read_b128 v[204:207], v139 offset:35840
	v_lshl_add_u64 v[172:173], s[38:39], 0, v[134:135]
	s_mov_b32 m0, s45
	s_nop 0
	global_load_lds_dwordx4 v[172:173], off
	v_lshl_add_u64 v[172:173], s[38:39], 0, v[130:131]
	s_mov_b32 m0, s54
	s_nop 0
	global_load_lds_dwordx4 v[172:173], off
	s_add_u32 s40, s40, 0x84000
	s_addc_u32 s41, s41, 0
	v_lshl_add_u64 v[172:173], s[40:41], 0, v[132:133]
	s_mov_b32 m0, s55
	s_nop 0
	global_load_lds_dwordx4 v[172:173], off
	v_lshl_add_u64 v[172:173], s[40:41], 0, v[128:129]
	s_mov_b32 m0, s56
	s_nop 0
	global_load_lds_dwordx4 v[172:173], off
	s_waitcnt lgkmcnt(11)
	ds_read_b128 v[208:211], v139 offset:36864
	ds_read_b128 v[212:215], v139 offset:37888
	ds_read_b128 v[216:219], v139 offset:38912
	ds_read_b128 v[220:223], v139 offset:39936
	s_waitcnt vmcnt(6)
	s_waitcnt lgkmcnt(8)
	s_barrier
	s_waitcnt lgkmcnt(0)
	v_mfma_f32_16x16x32_bf16 v[124:127], v[160:163], v[192:195], v[124:127]
	v_mfma_f32_16x16x32_bf16 v[120:123], v[168:171], v[192:195], v[120:123]
	v_mfma_f32_16x16x32_bf16 v[112:115], v[160:163], v[200:203], v[112:115]
	v_mfma_f32_16x16x32_bf16 v[108:111], v[168:171], v[200:203], v[108:111]
	v_mfma_f32_16x16x32_bf16 v[104:107], v[160:163], v[208:211], v[104:107]
	v_mfma_f32_16x16x32_bf16 v[96:99], v[168:171], v[208:211], v[96:99]
	v_mfma_f32_16x16x32_bf16 v[88:91], v[160:163], v[216:219], v[88:91]
	v_mfma_f32_16x16x32_bf16 v[80:83], v[168:171], v[216:219], v[80:83]
	v_mfma_f32_16x16x32_bf16 v[124:127], v[164:167], v[196:199], v[124:127]
	v_mfma_f32_16x16x32_bf16 v[120:123], v[188:191], v[196:199], v[120:123]
	v_mfma_f32_16x16x32_bf16 v[112:115], v[164:167], v[204:207], v[112:115]
	v_mfma_f32_16x16x32_bf16 v[108:111], v[188:191], v[204:207], v[108:111]
	v_mfma_f32_16x16x32_bf16 v[104:107], v[164:167], v[212:215], v[104:107]
	v_mfma_f32_16x16x32_bf16 v[96:99], v[188:191], v[212:215], v[96:99]
	v_mfma_f32_16x16x32_bf16 v[88:91], v[164:167], v[220:223], v[88:91]
	v_mfma_f32_16x16x32_bf16 v[80:83], v[188:191], v[220:223], v[80:83]
	v_mfma_f32_16x16x32_bf16 v[116:119], v[224:227], v[192:195], v[116:119]
	v_mfma_f32_16x16x32_bf16 v[100:103], v[232:235], v[192:195], v[100:103]
	v_mfma_f32_16x16x32_bf16 v[92:95], v[224:227], v[200:203], v[92:95]
	v_mfma_f32_16x16x32_bf16 v[84:87], v[232:235], v[200:203], v[84:87]
	v_mfma_f32_16x16x32_bf16 v[76:79], v[224:227], v[208:211], v[76:79]
	v_mfma_f32_16x16x32_bf16 v[72:75], v[232:235], v[208:211], v[72:75]
	v_mfma_f32_16x16x32_bf16 v[68:71], v[224:227], v[216:219], v[68:71]
	v_mfma_f32_16x16x32_bf16 v[64:67], v[232:235], v[216:219], v[64:67]
	v_mfma_f32_16x16x32_bf16 v[116:119], v[228:231], v[196:199], v[116:119]
	v_mfma_f32_16x16x32_bf16 v[100:103], v[236:239], v[196:199], v[100:103]
	v_mfma_f32_16x16x32_bf16 v[92:95], v[228:231], v[204:207], v[92:95]
	v_mfma_f32_16x16x32_bf16 v[84:87], v[236:239], v[204:207], v[84:87]
	v_mfma_f32_16x16x32_bf16 v[76:79], v[228:231], v[212:215], v[76:79]
	v_mfma_f32_16x16x32_bf16 v[72:75], v[236:239], v[212:215], v[72:75]
	v_mfma_f32_16x16x32_bf16 v[68:71], v[228:231], v[220:223], v[68:71]
	v_mfma_f32_16x16x32_bf16 v[64:67], v[236:239], v[220:223], v[64:67]
	s_barrier
	ds_read_b128 v[192:195], v139 offset:49152
	ds_read_b128 v[196:199], v139 offset:50176
	ds_read_b128 v[200:203], v139 offset:51200
	ds_read_b128 v[204:207], v139 offset:52224
	ds_read_b128 v[208:211], v139 offset:53248
	ds_read_b128 v[212:215], v139 offset:54272
	ds_read_b128 v[216:219], v139 offset:55296
	ds_read_b128 v[220:223], v139 offset:56320
	s_add_u32 s38, s38, 0x84000
	s_addc_u32 s39, s39, 0
	v_lshl_add_u64 v[172:173], s[38:39], 0, v[134:135]
	s_mov_b32 m0, s57
	s_nop 0
	global_load_lds_dwordx4 v[172:173], off
	v_lshl_add_u64 v[172:173], s[38:39], 0, v[130:131]
	s_mov_b32 m0, s58
	s_nop 0
	global_load_lds_dwordx4 v[172:173], off
	s_add_u32 s36, s89, s90
	s_addc_u32 s37, s88, 0
	v_lshl_add_u64 v[172:173], s[36:37], 0, v[132:133]
	s_mov_b32 m0, s62
	s_nop 0
	global_load_lds_dwordx4 v[172:173], off
	v_lshl_add_u64 v[172:173], s[36:37], 0, v[128:129]
	s_mov_b32 m0, s63
	s_nop 0
	global_load_lds_dwordx4 v[172:173], off
	s_waitcnt vmcnt(4)
	s_barrier
	s_waitcnt lgkmcnt(0)
	v_mfma_f32_16x16x32_bf16 v[60:63], v[160:163], v[192:195], v[60:63]
	v_mfma_f32_16x16x32_bf16 v[56:59], v[168:171], v[192:195], v[56:59]
	v_mfma_f32_16x16x32_bf16 v[52:55], v[160:163], v[200:203], v[52:55]
	v_mfma_f32_16x16x32_bf16 v[48:51], v[168:171], v[200:203], v[48:51]
	v_mfma_f32_16x16x32_bf16 v[40:43], v[160:163], v[208:211], v[40:43]
	v_mfma_f32_16x16x32_bf16 v[36:39], v[168:171], v[208:211], v[36:39]
	v_mfma_f32_16x16x32_bf16 v[24:27], v[160:163], v[216:219], v[24:27]
	v_mfma_f32_16x16x32_bf16 v[20:23], v[168:171], v[216:219], v[20:23]
	v_mfma_f32_16x16x32_bf16 v[60:63], v[164:167], v[196:199], v[60:63]
	v_mfma_f32_16x16x32_bf16 v[56:59], v[188:191], v[196:199], v[56:59]
	v_mfma_f32_16x16x32_bf16 v[52:55], v[164:167], v[204:207], v[52:55]
	v_mfma_f32_16x16x32_bf16 v[48:51], v[188:191], v[204:207], v[48:51]
	v_mfma_f32_16x16x32_bf16 v[40:43], v[164:167], v[212:215], v[40:43]
	v_mfma_f32_16x16x32_bf16 v[36:39], v[188:191], v[212:215], v[36:39]
	v_mfma_f32_16x16x32_bf16 v[24:27], v[164:167], v[220:223], v[24:27]
	v_mfma_f32_16x16x32_bf16 v[20:23], v[188:191], v[220:223], v[20:23]
	v_mfma_f32_16x16x32_bf16 v[44:47], v[224:227], v[192:195], v[44:47]
	v_mfma_f32_16x16x32_bf16 v[32:35], v[232:235], v[192:195], v[32:35]
	v_mfma_f32_16x16x32_bf16 v[28:31], v[224:227], v[200:203], v[28:31]
	v_mfma_f32_16x16x32_bf16 v[16:19], v[232:235], v[200:203], v[16:19]
	v_mfma_f32_16x16x32_bf16 v[12:15], v[224:227], v[208:211], v[12:15]
	v_mfma_f32_16x16x32_bf16 v[8:11], v[232:235], v[208:211], v[8:11]
	v_mfma_f32_16x16x32_bf16 v[4:7], v[224:227], v[216:219], v[4:7]
	v_mfma_f32_16x16x32_bf16 v[0:3], v[232:235], v[216:219], v[0:3]
	v_mfma_f32_16x16x32_bf16 v[44:47], v[228:231], v[196:199], v[44:47]
	v_mfma_f32_16x16x32_bf16 v[32:35], v[236:239], v[196:199], v[32:35]
	v_mfma_f32_16x16x32_bf16 v[28:31], v[228:231], v[204:207], v[28:31]
	v_mfma_f32_16x16x32_bf16 v[16:19], v[236:239], v[204:207], v[16:19]
	v_mfma_f32_16x16x32_bf16 v[12:15], v[228:231], v[212:215], v[12:15]
	v_mfma_f32_16x16x32_bf16 v[8:11], v[236:239], v[212:215], v[8:11]
	v_mfma_f32_16x16x32_bf16 v[4:7], v[228:231], v[220:223], v[4:7]
	v_mfma_f32_16x16x32_bf16 v[0:3], v[236:239], v[220:223], v[0:3]
	s_addk_i32 s85, 0x100
	s_cmp_gt_u32 s86, 29
	s_mov_b32 s86, s87
	s_barrier
	s_cbranch_scc0 .LBB0_388
	s_lshl_b32 s36, s80, 8
	v_lshl_add_u32 v137, s61, 8, v136
	v_or_b32_e32 v160, s36, v138
	v_ashrrev_i32_e32 v161, 31, v160
	v_mad_i64_i32 v[162:163], s[12:13], s59, v137, 0
	v_lshl_add_u64 v[164:165], v[162:163], 1, s[42:43]
	v_lshlrev_b64 v[162:163], 1, v[160:161]
	v_lshl_add_u64 v[168:169], v[164:165], 0, v[162:163]
	v_cvt_pk_bf16_f32 v164, v124, v125
	v_cvt_pk_bf16_f32 v165, v126, v127
	v_cvt_pk_bf16_f32 v166, v120, v121
	v_cvt_pk_bf16_f32 v167, v122, v123
	global_store_dwordx4 v[168:169], v[164:167], off
	v_or_b32_e32 v144, 16, v137
	s_cmp_lt_i32 s61, 16
	v_cvt_pk_bf16_f32 v164, v116, v117
	v_cvt_pk_bf16_f32 v165, v118, v119
	v_cvt_pk_bf16_f32 v166, v100, v101
	v_cvt_pk_bf16_f32 v167, v102, v103
	global_store_dwordx4 v[168:169], v[164:167], off offset:256
	s_nop 1
	v_mad_i64_i32 v[164:165], s[12:13], s59, v144, 0
	v_lshl_add_u64 v[164:165], v[164:165], 1, s[42:43]
	v_lshl_add_u64 v[168:169], v[164:165], 0, v[162:163]
	v_cvt_pk_bf16_f32 v164, v112, v113
	v_cvt_pk_bf16_f32 v165, v114, v115
	v_cvt_pk_bf16_f32 v166, v108, v109
	v_cvt_pk_bf16_f32 v167, v110, v111
	global_store_dwordx4 v[168:169], v[164:167], off
	v_or_b32_e32 v144, 32, v137
	s_nop 0
	v_cvt_pk_bf16_f32 v164, v92, v93
	v_cvt_pk_bf16_f32 v165, v94, v95
	v_cvt_pk_bf16_f32 v166, v84, v85
	v_cvt_pk_bf16_f32 v167, v86, v87
	global_store_dwordx4 v[168:169], v[164:167], off offset:256
	s_nop 1
	v_mad_i64_i32 v[164:165], s[12:13], s59, v144, 0
	v_lshl_add_u64 v[164:165], v[164:165], 1, s[42:43]
	v_lshl_add_u64 v[168:169], v[164:165], 0, v[162:163]
	v_cvt_pk_bf16_f32 v164, v104, v105
	v_cvt_pk_bf16_f32 v165, v106, v107
	v_cvt_pk_bf16_f32 v166, v96, v97
	v_cvt_pk_bf16_f32 v167, v98, v99
	global_store_dwordx4 v[168:169], v[164:167], off
	v_or_b32_e32 v144, 48, v137
	s_nop 0
	v_cvt_pk_bf16_f32 v164, v76, v77
	v_cvt_pk_bf16_f32 v165, v78, v79
	v_cvt_pk_bf16_f32 v166, v72, v73
	v_cvt_pk_bf16_f32 v167, v74, v75
	global_store_dwordx4 v[168:169], v[164:167], off offset:256
	s_nop 1
	v_mad_i64_i32 v[164:165], s[12:13], s59, v144, 0
	v_lshl_add_u64 v[164:165], v[164:165], 1, s[42:43]
	v_lshl_add_u64 v[168:169], v[164:165], 0, v[162:163]
	v_cvt_pk_bf16_f32 v164, v88, v89
	v_cvt_pk_bf16_f32 v165, v90, v91
	v_cvt_pk_bf16_f32 v166, v80, v81
	v_cvt_pk_bf16_f32 v167, v82, v83
	global_store_dwordx4 v[168:169], v[164:167], off
	v_add_u32_e32 v144, 0x80, v137
	s_nop 0
	v_cvt_pk_bf16_f32 v164, v68, v69
	v_cvt_pk_bf16_f32 v165, v70, v71
	v_cvt_pk_bf16_f32 v166, v64, v65
	v_cvt_pk_bf16_f32 v167, v66, v67
	global_store_dwordx4 v[168:169], v[164:167], off offset:256
	s_nop 1
	v_mad_i64_i32 v[164:165], s[12:13], s59, v144, 0
	v_lshl_add_u64 v[164:165], v[164:165], 1, s[42:43]
	v_lshl_add_u64 v[168:169], v[164:165], 0, v[162:163]
	v_cvt_pk_bf16_f32 v164, v60, v61
	v_cvt_pk_bf16_f32 v165, v62, v63
	v_cvt_pk_bf16_f32 v166, v56, v57
	v_cvt_pk_bf16_f32 v167, v58, v59
	global_store_dwordx4 v[168:169], v[164:167], off
	v_add_u32_e32 v144, 0x90, v137
	s_nop 0
	v_cvt_pk_bf16_f32 v164, v44, v45
	v_cvt_pk_bf16_f32 v165, v46, v47
	v_cvt_pk_bf16_f32 v166, v32, v33
	v_cvt_pk_bf16_f32 v167, v34, v35
	global_store_dwordx4 v[168:169], v[164:167], off offset:256
	s_nop 1
	v_mad_i64_i32 v[164:165], s[12:13], s59, v144, 0
	v_lshl_add_u64 v[164:165], v[164:165], 1, s[42:43]
	v_lshl_add_u64 v[168:169], v[164:165], 0, v[162:163]
	v_cvt_pk_bf16_f32 v164, v52, v53
	v_cvt_pk_bf16_f32 v165, v54, v55
	v_cvt_pk_bf16_f32 v166, v48, v49
	v_cvt_pk_bf16_f32 v167, v50, v51
	global_store_dwordx4 v[168:169], v[164:167], off
	v_add_u32_e32 v144, 0xa0, v137
	v_add_u32_e32 v137, 0xb0, v137
	v_cvt_pk_bf16_f32 v164, v28, v29
	v_cvt_pk_bf16_f32 v165, v30, v31
	v_cvt_pk_bf16_f32 v166, v16, v17
	v_cvt_pk_bf16_f32 v167, v18, v19
	global_store_dwordx4 v[168:169], v[164:167], off offset:256
	s_nop 1
	v_mad_i64_i32 v[164:165], s[12:13], s59, v144, 0
	v_lshl_add_u64 v[164:165], v[164:165], 1, s[42:43]
	v_lshl_add_u64 v[168:169], v[164:165], 0, v[162:163]
	v_cvt_pk_bf16_f32 v164, v40, v41
	v_cvt_pk_bf16_f32 v165, v42, v43
	v_cvt_pk_bf16_f32 v166, v36, v37
	v_cvt_pk_bf16_f32 v167, v38, v39
	global_store_dwordx4 v[168:169], v[164:167], off
	s_nop 1
	v_cvt_pk_bf16_f32 v164, v12, v13
	v_cvt_pk_bf16_f32 v165, v14, v15
	v_cvt_pk_bf16_f32 v166, v8, v9
	v_cvt_pk_bf16_f32 v167, v10, v11
	global_store_dwordx4 v[168:169], v[164:167], off offset:256
	s_nop 1
	v_mad_i64_i32 v[164:165], s[12:13], s59, v137, 0
	s_cselect_b64 s[12:13], -1, 0
	v_lshl_add_u64 v[164:165], v[164:165], 1, s[42:43]
	s_and_b64 s[12:13], s[8:9], s[12:13]
	v_lshl_add_u64 v[166:167], v[164:165], 0, v[162:163]
	v_cvt_pk_bf16_f32 v162, v24, v25
	v_cvt_pk_bf16_f32 v163, v26, v27
	v_cvt_pk_bf16_f32 v164, v20, v21
	v_cvt_pk_bf16_f32 v165, v22, v23
	s_andn2_b64 vcc, exec, s[12:13]
	global_store_dwordx4 v[166:167], v[162:165], off
	s_nop 1
	v_cvt_pk_bf16_f32 v162, v4, v5
	v_cvt_pk_bf16_f32 v163, v6, v7
	v_cvt_pk_bf16_f32 v164, v0, v1
	v_cvt_pk_bf16_f32 v165, v2, v3
	global_store_dwordx4 v[166:167], v[162:165], off offset:256
	s_cbranch_vccnz .LBB0_380
	s_cmp_lt_i32 s80, 5
	s_cbranch_scc1 .LBB0_394
	s_cmp_eq_u32 s80, 5
	s_mov_b64 s[14:15], -1
	s_cbranch_scc0 .LBB0_393
	s_mov_b64 s[14:15], 0

.LBB0_494:
	s_cmpk_eq_i32 s85, 0xf80
	s_cselect_b32 s37, s5, s13
	s_cselect_b32 s36, s4, s12
	s_cselect_b32 s88, s7, s11
	s_cselect_b32 s89, s6, s10
	s_add_i32 s14, s86, 3
	s_cmpk_eq_i32 s85, 0xf80
	s_cselect_b32 s14, 1, s14
	s_add_i32 s87, s86, 2
	s_cmpk_eq_i32 s85, 0xf80
	s_cselect_b32 s15, 0, s87
	s_add_i32 s15, s15, s64
	s_add_i32 s14, s14, s64
	s_add_i32 s38, s66, s85
	s_lshl_b32 s15, s15, 7
	s_lshl_b32 s14, s14, 7
	s_and_b32 s91, s38, 0xf80
	s_and_b32 s92, s15, 0xf80
	s_and_b32 s90, s14, 0xf80
	s_add_u32 s38, s89, s92
	s_addc_u32 s39, s88, 0
	s_add_u32 s36, s36, s92
	s_addc_u32 s37, s37, 0
	s_add_u32 s14, s10, s91
	s_addc_u32 s15, s11, 0
	s_add_u32 s14, s14, 0x84000
	s_addc_u32 s15, s15, 0
	s_add_u32 s92, s12, s91
	s_addc_u32 s93, s13, 0
	v_add_u32_e32 v222, 0x10000, v140
	ds_read_b128 v[134:137], v222
	ds_read_b128 v[148:151], v222 offset:1024
	ds_read_b128 v[152:155], v222 offset:2048
	ds_read_b128 v[156:159], v222 offset:3072
	v_add_u32_e32 v223, 0x14000, v140
	ds_read_b128 v[204:207], v223
	ds_read_b128 v[208:211], v223 offset:1024
	ds_read_b128 v[212:215], v223 offset:2048
	ds_read_b128 v[216:219], v223 offset:3072
	ds_read_b128 v[160:163], v139
	ds_read_b128 v[164:167], v139 offset:1024
	ds_read_b128 v[168:171], v139 offset:2048
	ds_read_b128 v[172:175], v139 offset:3072
	v_lshl_add_u64 v[220:221], s[92:93], 0, v[132:133]
	s_mov_b32 m0, s76
	s_nop 0
	global_load_lds_dwordx4 v[220:221], off
	v_lshl_add_u64 v[220:221], s[92:93], 0, v[130:131]
	s_mov_b32 m0, s77
	s_nop 0
	global_load_lds_dwordx4 v[220:221], off
	v_lshl_add_u64 v[220:221], s[14:15], 0, v[144:145]
	s_mov_b32 m0, s78
	s_nop 0
	global_load_lds_dwordx4 v[220:221], off
	v_lshl_add_u64 v[220:221], s[14:15], 0, v[128:129]
	s_mov_b32 m0, s79
	s_nop 0
	global_load_lds_dwordx4 v[220:221], off
	s_waitcnt lgkmcnt(11)
	ds_read_b128 v[188:191], v139 offset:4096
	ds_read_b128 v[192:195], v139 offset:5120
	ds_read_b128 v[196:199], v139 offset:6144
	ds_read_b128 v[200:203], v139 offset:7168
	s_waitcnt vmcnt(6)
	s_waitcnt lgkmcnt(8)
	s_barrier
	s_waitcnt lgkmcnt(0)
	v_mfma_f32_16x16x32_bf16 v[124:127], v[134:137], v[160:163], v[124:127]
	v_mfma_f32_16x16x32_bf16 v[120:123], v[152:155], v[160:163], v[120:123]
	v_mfma_f32_16x16x32_bf16 v[116:119], v[134:137], v[168:171], v[116:119]
	v_mfma_f32_16x16x32_bf16 v[108:111], v[152:155], v[168:171], v[108:111]
	v_mfma_f32_16x16x32_bf16 v[100:103], v[134:137], v[188:191], v[100:103]
	v_mfma_f32_16x16x32_bf16 v[92:95], v[152:155], v[188:191], v[92:95]
	v_mfma_f32_16x16x32_bf16 v[84:87], v[134:137], v[196:199], v[84:87]
	v_mfma_f32_16x16x32_bf16 v[76:79], v[152:155], v[196:199], v[76:79]
	v_mfma_f32_16x16x32_bf16 v[124:127], v[148:151], v[164:167], v[124:127]
	v_mfma_f32_16x16x32_bf16 v[120:123], v[156:159], v[164:167], v[120:123]
	v_mfma_f32_16x16x32_bf16 v[116:119], v[148:151], v[172:175], v[116:119]
	v_mfma_f32_16x16x32_bf16 v[108:111], v[156:159], v[172:175], v[108:111]
	v_mfma_f32_16x16x32_bf16 v[100:103], v[148:151], v[192:195], v[100:103]
	v_mfma_f32_16x16x32_bf16 v[92:95], v[156:159], v[192:195], v[92:95]
	v_mfma_f32_16x16x32_bf16 v[84:87], v[148:151], v[200:203], v[84:87]
	v_mfma_f32_16x16x32_bf16 v[76:79], v[156:159], v[200:203], v[76:79]
	v_mfma_f32_16x16x32_bf16 v[112:115], v[204:207], v[160:163], v[112:115]
	v_mfma_f32_16x16x32_bf16 v[104:107], v[212:215], v[160:163], v[104:107]
	v_mfma_f32_16x16x32_bf16 v[96:99], v[204:207], v[168:171], v[96:99]
	v_mfma_f32_16x16x32_bf16 v[88:91], v[212:215], v[168:171], v[88:91]
	v_mfma_f32_16x16x32_bf16 v[80:83], v[204:207], v[188:191], v[80:83]
	v_mfma_f32_16x16x32_bf16 v[72:75], v[212:215], v[188:191], v[72:75]
	v_mfma_f32_16x16x32_bf16 v[68:71], v[204:207], v[196:199], v[68:71]
	v_mfma_f32_16x16x32_bf16 v[64:67], v[212:215], v[196:199], v[64:67]
	v_mfma_f32_16x16x32_bf16 v[112:115], v[208:211], v[164:167], v[112:115]
	v_mfma_f32_16x16x32_bf16 v[104:107], v[216:219], v[164:167], v[104:107]
	v_mfma_f32_16x16x32_bf16 v[96:99], v[208:211], v[172:175], v[96:99]
	v_mfma_f32_16x16x32_bf16 v[88:91], v[216:219], v[172:175], v[88:91]
	v_mfma_f32_16x16x32_bf16 v[80:83], v[208:211], v[192:195], v[80:83]
	v_mfma_f32_16x16x32_bf16 v[72:75], v[216:219], v[192:195], v[72:75]
	v_mfma_f32_16x16x32_bf16 v[68:71], v[208:211], v[200:203], v[68:71]
	v_mfma_f32_16x16x32_bf16 v[64:67], v[216:219], v[200:203], v[64:67]
	s_barrier
	ds_read_b128 v[160:163], v139 offset:16384
	ds_read_b128 v[164:167], v139 offset:17408
	ds_read_b128 v[168:171], v139 offset:18432
	ds_read_b128 v[172:175], v139 offset:19456
	ds_read_b128 v[188:191], v139 offset:20480
	ds_read_b128 v[192:195], v139 offset:21504
	ds_read_b128 v[196:199], v139 offset:22528
	ds_read_b128 v[200:203], v139 offset:23552
	s_add_u32 s92, s92, 0x84000
	s_addc_u32 s93, s93, 0
	v_lshl_add_u64 v[220:221], s[92:93], 0, v[132:133]
	s_add_i32 m0, s41, 0xc000
	s_nop 0
	global_load_lds_dwordx4 v[220:221], off
	v_lshl_add_u64 v[220:221], s[92:93], 0, v[130:131]
	s_add_i32 m0, s41, 0xe000
	s_nop 0
	global_load_lds_dwordx4 v[220:221], off
	v_lshl_add_u64 v[220:221], s[38:39], 0, v[144:145]
	s_mov_b32 m0, s44
	s_nop 0
	global_load_lds_dwordx4 v[220:221], off
	v_lshl_add_u64 v[220:221], s[38:39], 0, v[128:129]
	s_mov_b32 m0, s45
	s_nop 0
	global_load_lds_dwordx4 v[220:221], off
	s_waitcnt vmcnt(4)
	s_barrier
	s_waitcnt lgkmcnt(0)
	v_mfma_f32_16x16x32_bf16 v[60:63], v[134:137], v[160:163], v[60:63]
	v_mfma_f32_16x16x32_bf16 v[56:59], v[152:155], v[160:163], v[56:59]
	v_mfma_f32_16x16x32_bf16 v[52:55], v[134:137], v[168:171], v[52:55]
	v_mfma_f32_16x16x32_bf16 v[44:47], v[152:155], v[168:171], v[44:47]
	v_mfma_f32_16x16x32_bf16 v[36:39], v[134:137], v[188:191], v[36:39]
	v_mfma_f32_16x16x32_bf16 v[28:31], v[152:155], v[188:191], v[28:31]
	v_mfma_f32_16x16x32_bf16 v[20:23], v[134:137], v[196:199], v[20:23]
	v_mfma_f32_16x16x32_bf16 v[12:15], v[152:155], v[196:199], v[12:15]
	v_mfma_f32_16x16x32_bf16 v[60:63], v[148:151], v[164:167], v[60:63]
	v_mfma_f32_16x16x32_bf16 v[56:59], v[156:159], v[164:167], v[56:59]
	v_mfma_f32_16x16x32_bf16 v[52:55], v[148:151], v[172:175], v[52:55]
	v_mfma_f32_16x16x32_bf16 v[44:47], v[156:159], v[172:175], v[44:47]
	v_mfma_f32_16x16x32_bf16 v[36:39], v[148:151], v[192:195], v[36:39]
	v_mfma_f32_16x16x32_bf16 v[28:31], v[156:159], v[192:195], v[28:31]
	v_mfma_f32_16x16x32_bf16 v[20:23], v[148:151], v[200:203], v[20:23]
	v_mfma_f32_16x16x32_bf16 v[12:15], v[156:159], v[200:203], v[12:15]
	v_mfma_f32_16x16x32_bf16 v[48:51], v[204:207], v[160:163], v[48:51]
	v_mfma_f32_16x16x32_bf16 v[40:43], v[212:215], v[160:163], v[40:43]
	v_mfma_f32_16x16x32_bf16 v[32:35], v[204:207], v[168:171], v[32:35]
	v_mfma_f32_16x16x32_bf16 v[24:27], v[212:215], v[168:171], v[24:27]
	v_mfma_f32_16x16x32_bf16 v[16:19], v[204:207], v[188:191], v[16:19]
	v_mfma_f32_16x16x32_bf16 v[8:11], v[212:215], v[188:191], v[8:11]
	v_mfma_f32_16x16x32_bf16 v[4:7], v[204:207], v[196:199], v[4:7]
	v_mfma_f32_16x16x32_bf16 v[0:3], v[212:215], v[196:199], v[0:3]
	v_mfma_f32_16x16x32_bf16 v[48:51], v[208:211], v[164:167], v[48:51]
	v_mfma_f32_16x16x32_bf16 v[40:43], v[216:219], v[164:167], v[40:43]
	v_mfma_f32_16x16x32_bf16 v[32:35], v[208:211], v[172:175], v[32:35]
	v_mfma_f32_16x16x32_bf16 v[24:27], v[216:219], v[172:175], v[24:27]
	v_mfma_f32_16x16x32_bf16 v[16:19], v[208:211], v[192:195], v[16:19]
	v_mfma_f32_16x16x32_bf16 v[8:11], v[216:219], v[192:195], v[8:11]
	v_mfma_f32_16x16x32_bf16 v[4:7], v[208:211], v[200:203], v[4:7]
	v_mfma_f32_16x16x32_bf16 v[0:3], v[216:219], v[200:203], v[0:3]
	s_barrier
	v_add_u32_e32 v222, 0x18000, v140
	ds_read_b128 v[134:137], v222
	ds_read_b128 v[148:151], v222 offset:1024
	ds_read_b128 v[152:155], v222 offset:2048
	ds_read_b128 v[156:159], v222 offset:3072
	v_add_u32_e32 v223, 0x1c000, v140
	ds_read_b128 v[204:207], v223
	ds_read_b128 v[208:211], v223 offset:1024
	ds_read_b128 v[212:215], v223 offset:2048
	ds_read_b128 v[216:219], v223 offset:3072
	ds_read_b128 v[160:163], v139 offset:32768
	ds_read_b128 v[164:167], v139 offset:33792
	ds_read_b128 v[168:171], v139 offset:34816
	ds_read_b128 v[172:175], v139 offset:35840
	v_lshl_add_u64 v[220:221], s[36:37], 0, v[132:133]
	s_mov_b32 m0, s41
	s_nop 0
	global_load_lds_dwordx4 v[220:221], off
	v_lshl_add_u64 v[220:221], s[36:37], 0, v[130:131]
	s_mov_b32 m0, s59
	s_nop 0
	global_load_lds_dwordx4 v[220:221], off
	s_add_u32 s38, s38, 0x84000
	s_addc_u32 s39, s39, 0
	v_lshl_add_u64 v[220:221], s[38:39], 0, v[144:145]
	s_mov_b32 m0, s60
	s_nop 0
	global_load_lds_dwordx4 v[220:221], off
	v_lshl_add_u64 v[220:221], s[38:39], 0, v[128:129]
	s_mov_b32 m0, s61
	s_nop 0
	global_load_lds_dwordx4 v[220:221], off
	s_waitcnt lgkmcnt(11)
	ds_read_b128 v[188:191], v139 offset:36864
	ds_read_b128 v[192:195], v139 offset:37888
	ds_read_b128 v[196:199], v139 offset:38912
	ds_read_b128 v[200:203], v139 offset:39936
	s_waitcnt vmcnt(6)
	s_waitcnt lgkmcnt(8)
	s_barrier
	s_waitcnt lgkmcnt(0)
	v_mfma_f32_16x16x32_bf16 v[124:127], v[134:137], v[160:163], v[124:127]
	v_mfma_f32_16x16x32_bf16 v[120:123], v[152:155], v[160:163], v[120:123]
	v_mfma_f32_16x16x32_bf16 v[116:119], v[134:137], v[168:171], v[116:119]
	v_mfma_f32_16x16x32_bf16 v[108:111], v[152:155], v[168:171], v[108:111]
	v_mfma_f32_16x16x32_bf16 v[100:103], v[134:137], v[188:191], v[100:103]
	v_mfma_f32_16x16x32_bf16 v[92:95], v[152:155], v[188:191], v[92:95]
	v_mfma_f32_16x16x32_bf16 v[84:87], v[134:137], v[196:199], v[84:87]
	v_mfma_f32_16x16x32_bf16 v[76:79], v[152:155], v[196:199], v[76:79]
	v_mfma_f32_16x16x32_bf16 v[124:127], v[148:151], v[164:167], v[124:127]
	v_mfma_f32_16x16x32_bf16 v[120:123], v[156:159], v[164:167], v[120:123]
	v_mfma_f32_16x16x32_bf16 v[116:119], v[148:151], v[172:175], v[116:119]
	v_mfma_f32_16x16x32_bf16 v[108:111], v[156:159], v[172:175], v[108:111]
	v_mfma_f32_16x16x32_bf16 v[100:103], v[148:151], v[192:195], v[100:103]
	v_mfma_f32_16x16x32_bf16 v[92:95], v[156:159], v[192:195], v[92:95]
	v_mfma_f32_16x16x32_bf16 v[84:87], v[148:151], v[200:203], v[84:87]
	v_mfma_f32_16x16x32_bf16 v[76:79], v[156:159], v[200:203], v[76:79]
	v_mfma_f32_16x16x32_bf16 v[112:115], v[204:207], v[160:163], v[112:115]
	v_mfma_f32_16x16x32_bf16 v[104:107], v[212:215], v[160:163], v[104:107]
	v_mfma_f32_16x16x32_bf16 v[96:99], v[204:207], v[168:171], v[96:99]
	v_mfma_f32_16x16x32_bf16 v[88:91], v[212:215], v[168:171], v[88:91]
	v_mfma_f32_16x16x32_bf16 v[80:83], v[204:207], v[188:191], v[80:83]
	v_mfma_f32_16x16x32_bf16 v[72:75], v[212:215], v[188:191], v[72:75]
	v_mfma_f32_16x16x32_bf16 v[68:71], v[204:207], v[196:199], v[68:71]
	v_mfma_f32_16x16x32_bf16 v[64:67], v[212:215], v[196:199], v[64:67]
	v_mfma_f32_16x16x32_bf16 v[112:115], v[208:211], v[164:167], v[112:115]
	v_mfma_f32_16x16x32_bf16 v[104:107], v[216:219], v[164:167], v[104:107]
	v_mfma_f32_16x16x32_bf16 v[96:99], v[208:211], v[172:175], v[96:99]
	v_mfma_f32_16x16x32_bf16 v[88:91], v[216:219], v[172:175], v[88:91]
	v_mfma_f32_16x16x32_bf16 v[80:83], v[208:211], v[192:195], v[80:83]
	v_mfma_f32_16x16x32_bf16 v[72:75], v[216:219], v[192:195], v[72:75]
	v_mfma_f32_16x16x32_bf16 v[68:71], v[208:211], v[200:203], v[68:71]
	v_mfma_f32_16x16x32_bf16 v[64:67], v[216:219], v[200:203], v[64:67]
	s_barrier
	ds_read_b128 v[160:163], v139 offset:49152
	ds_read_b128 v[164:167], v139 offset:50176
	ds_read_b128 v[168:171], v139 offset:51200
	ds_read_b128 v[172:175], v139 offset:52224
	ds_read_b128 v[188:191], v139 offset:53248
	ds_read_b128 v[192:195], v139 offset:54272
	ds_read_b128 v[196:199], v139 offset:55296
	ds_read_b128 v[200:203], v139 offset:56320
	s_add_u32 s36, s36, 0x84000
	s_addc_u32 s37, s37, 0
	v_lshl_add_u64 v[220:221], s[36:37], 0, v[132:133]
	s_mov_b32 m0, s62
	s_nop 0
	global_load_lds_dwordx4 v[220:221], off
	v_lshl_add_u64 v[220:221], s[36:37], 0, v[130:131]
	s_mov_b32 m0, s63
	s_nop 0
	global_load_lds_dwordx4 v[220:221], off
	s_add_u32 s14, s89, s90
	s_addc_u32 s15, s88, 0
	v_lshl_add_u64 v[220:221], s[14:15], 0, v[144:145]
	s_mov_b32 m0, s74
	s_nop 0
	global_load_lds_dwordx4 v[220:221], off
	v_lshl_add_u64 v[220:221], s[14:15], 0, v[128:129]
	s_mov_b32 m0, s75
	s_nop 0
	global_load_lds_dwordx4 v[220:221], off
	s_waitcnt vmcnt(4)
	s_barrier
	s_waitcnt lgkmcnt(0)
	v_mfma_f32_16x16x32_bf16 v[60:63], v[134:137], v[160:163], v[60:63]
	v_mfma_f32_16x16x32_bf16 v[56:59], v[152:155], v[160:163], v[56:59]
	v_mfma_f32_16x16x32_bf16 v[52:55], v[134:137], v[168:171], v[52:55]
	v_mfma_f32_16x16x32_bf16 v[44:47], v[152:155], v[168:171], v[44:47]
	v_mfma_f32_16x16x32_bf16 v[36:39], v[134:137], v[188:191], v[36:39]
	v_mfma_f32_16x16x32_bf16 v[28:31], v[152:155], v[188:191], v[28:31]
	v_mfma_f32_16x16x32_bf16 v[20:23], v[134:137], v[196:199], v[20:23]
	v_mfma_f32_16x16x32_bf16 v[12:15], v[152:155], v[196:199], v[12:15]
	v_mfma_f32_16x16x32_bf16 v[60:63], v[148:151], v[164:167], v[60:63]
	v_mfma_f32_16x16x32_bf16 v[56:59], v[156:159], v[164:167], v[56:59]
	v_mfma_f32_16x16x32_bf16 v[52:55], v[148:151], v[172:175], v[52:55]
	v_mfma_f32_16x16x32_bf16 v[44:47], v[156:159], v[172:175], v[44:47]
	v_mfma_f32_16x16x32_bf16 v[36:39], v[148:151], v[192:195], v[36:39]
	v_mfma_f32_16x16x32_bf16 v[28:31], v[156:159], v[192:195], v[28:31]
	v_mfma_f32_16x16x32_bf16 v[20:23], v[148:151], v[200:203], v[20:23]
	v_mfma_f32_16x16x32_bf16 v[12:15], v[156:159], v[200:203], v[12:15]
	v_mfma_f32_16x16x32_bf16 v[48:51], v[204:207], v[160:163], v[48:51]
	v_mfma_f32_16x16x32_bf16 v[40:43], v[212:215], v[160:163], v[40:43]
	v_mfma_f32_16x16x32_bf16 v[32:35], v[204:207], v[168:171], v[32:35]
	v_mfma_f32_16x16x32_bf16 v[24:27], v[212:215], v[168:171], v[24:27]
	v_mfma_f32_16x16x32_bf16 v[16:19], v[204:207], v[188:191], v[16:19]
	v_mfma_f32_16x16x32_bf16 v[8:11], v[212:215], v[188:191], v[8:11]
	v_mfma_f32_16x16x32_bf16 v[4:7], v[204:207], v[196:199], v[4:7]
	v_mfma_f32_16x16x32_bf16 v[0:3], v[212:215], v[196:199], v[0:3]
	v_mfma_f32_16x16x32_bf16 v[48:51], v[208:211], v[164:167], v[48:51]
	v_mfma_f32_16x16x32_bf16 v[40:43], v[216:219], v[164:167], v[40:43]
	v_mfma_f32_16x16x32_bf16 v[32:35], v[208:211], v[172:175], v[32:35]
	v_mfma_f32_16x16x32_bf16 v[24:27], v[216:219], v[172:175], v[24:27]
	v_mfma_f32_16x16x32_bf16 v[16:19], v[208:211], v[192:195], v[16:19]
	v_mfma_f32_16x16x32_bf16 v[8:11], v[216:219], v[192:195], v[8:11]
	v_mfma_f32_16x16x32_bf16 v[4:7], v[208:211], v[200:203], v[4:7]
	v_mfma_f32_16x16x32_bf16 v[0:3], v[216:219], v[200:203], v[0:3]
	s_addk_i32 s85, 0x100
	s_cmp_gt_u32 s86, 29
	s_mov_b32 s86, s87
	s_barrier
	s_cbranch_scc0 .LBB0_494
	v_readlane_b32 s10, v252, 58
	v_lshl_add_u32 v146, s84, 8, v138
	v_lshl_or_b32 v136, s83, 8, v141
	v_readlane_b32 s11, v252, 59
	v_ashrrev_i32_e32 v137, 31, v136
	v_cvt_pk_bf16_f32 v68, v68, v69
	v_cvt_pk_bf16_f32 v69, v70, v71
	v_cvt_pk_bf16_f32 v70, v64, v65
	v_add_u32_e32 v64, 0x80, v146
	v_mov_b64_e32 v[134:135], s[10:11]
	v_mad_i64_i32 v[142:143], s[10:11], v146, s70, v[134:135]
	v_lshlrev_b64 v[136:137], 1, v[136:137]
	v_cvt_pk_bf16_f32 v112, v112, v113
	v_cvt_pk_bf16_f32 v113, v114, v115
	v_cvt_pk_bf16_f32 v114, v104, v105
	v_or_b32_e32 v104, 16, v146
	v_mad_i64_i32 v[64:65], s[10:11], v64, s70, v[134:135]
	v_cvt_pk_bf16_f32 v48, v48, v49
	v_cvt_pk_bf16_f32 v49, v50, v51
	v_cvt_pk_bf16_f32 v50, v40, v41
	v_add_u32_e32 v40, 0x90, v146
	v_lshl_add_u64 v[142:143], v[142:143], 0, v[136:137]
	v_mad_i64_i32 v[104:105], s[10:11], v104, s70, v[134:135]
	v_cvt_pk_bf16_f32 v96, v96, v97
	v_cvt_pk_bf16_f32 v97, v98, v99
	v_cvt_pk_bf16_f32 v98, v88, v89
	v_or_b32_e32 v88, 32, v146
	v_lshl_add_u64 v[64:65], v[64:65], 0, v[136:137]
	v_mad_i64_i32 v[40:41], s[10:11], v40, s70, v[134:135]
	v_cvt_pk_bf16_f32 v32, v32, v33
	v_cvt_pk_bf16_f32 v33, v34, v35
	v_cvt_pk_bf16_f32 v34, v24, v25
	v_add_u32_e32 v24, 0xa0, v146
	v_cvt_pk_bf16_f32 v115, v106, v107
	global_store_dwordx4 v[142:143], v[112:115], off offset:256
	v_mad_i64_i32 v[88:89], s[10:11], v88, s70, v[134:135]
	s_nop 0
	v_lshl_add_u64 v[112:113], v[104:105], 0, v[136:137]
	v_cvt_pk_bf16_f32 v80, v80, v81
	v_cvt_pk_bf16_f32 v81, v82, v83
	v_cvt_pk_bf16_f32 v82, v72, v73
	v_or_b32_e32 v72, 48, v146
	v_cvt_pk_bf16_f32 v51, v42, v43
	global_store_dwordx4 v[64:65], v[48:51], off offset:256
	v_mad_i64_i32 v[24:25], s[10:11], v24, s70, v[134:135]
	s_nop 0
	v_lshl_add_u64 v[48:49], v[40:41], 0, v[136:137]
	v_cvt_pk_bf16_f32 v16, v16, v17
	v_cvt_pk_bf16_f32 v17, v18, v19
	v_cvt_pk_bf16_f32 v18, v8, v9
	v_add_u32_e32 v8, 0xb0, v146
	v_cvt_pk_bf16_f32 v99, v90, v91
	global_store_dwordx4 v[112:113], v[96:99], off offset:256
	v_mad_i64_i32 v[72:73], s[10:11], v72, s70, v[134:135]
	s_nop 0
	v_lshl_add_u64 v[96:97], v[88:89], 0, v[136:137]
	v_cvt_pk_bf16_f32 v35, v26, v27
	global_store_dwordx4 v[48:49], v[32:35], off offset:256
	v_mad_i64_i32 v[8:9], s[10:11], v8, s70, v[134:135]
	s_nop 0
	v_lshl_add_u64 v[32:33], v[24:25], 0, v[136:137]
	v_cvt_pk_bf16_f32 v83, v74, v75
	global_store_dwordx4 v[96:97], v[80:83], off offset:256
	v_cvt_pk_bf16_f32 v19, v10, v11
	global_store_dwordx4 v[32:33], v[16:19], off offset:256
	s_and_b64 vcc, exec, s[0:1]
	v_lshl_add_u64 v[80:81], v[72:73], 0, v[136:137]
	v_lshl_add_u64 v[16:17], v[8:9], 0, v[136:137]
	s_mov_b32 s83, s81
	s_mov_b32 s84, s82
	s_mov_b64 s[10:11], s[6:7]
	s_mov_b64 s[12:13], s[4:5]
	v_cvt_pk_bf16_f32 v124, v124, v125
	v_cvt_pk_bf16_f32 v125, v126, v127
	v_cvt_pk_bf16_f32 v126, v120, v121
	v_cvt_pk_bf16_f32 v127, v122, v123
	global_store_dwordx4 v[142:143], v[124:127], off
	v_cvt_pk_bf16_f32 v104, v116, v117
	v_cvt_pk_bf16_f32 v105, v118, v119
	v_cvt_pk_bf16_f32 v106, v108, v109
	v_cvt_pk_bf16_f32 v107, v110, v111
	global_store_dwordx4 v[112:113], v[104:107], off
	v_cvt_pk_bf16_f32 v88, v100, v101
	v_cvt_pk_bf16_f32 v89, v102, v103
	v_cvt_pk_bf16_f32 v90, v92, v93
	v_cvt_pk_bf16_f32 v91, v94, v95
	global_store_dwordx4 v[96:97], v[88:91], off
	v_cvt_pk_bf16_f32 v72, v84, v85
	v_cvt_pk_bf16_f32 v73, v86, v87
	v_cvt_pk_bf16_f32 v74, v76, v77
	v_cvt_pk_bf16_f32 v75, v78, v79
	global_store_dwordx4 v[80:81], v[72:75], off
	v_cvt_pk_bf16_f32 v71, v66, v67
	global_store_dwordx4 v[80:81], v[68:71], off offset:256
	v_cvt_pk_bf16_f32 v60, v60, v61
	v_cvt_pk_bf16_f32 v61, v62, v63
	v_cvt_pk_bf16_f32 v62, v56, v57
	v_cvt_pk_bf16_f32 v63, v58, v59
	global_store_dwordx4 v[64:65], v[60:63], off
	v_cvt_pk_bf16_f32 v40, v52, v53
	v_cvt_pk_bf16_f32 v41, v54, v55
	v_cvt_pk_bf16_f32 v42, v44, v45
	v_cvt_pk_bf16_f32 v43, v46, v47
	global_store_dwordx4 v[48:49], v[40:43], off
	v_cvt_pk_bf16_f32 v24, v36, v37
	v_cvt_pk_bf16_f32 v25, v38, v39
	v_cvt_pk_bf16_f32 v26, v28, v29
	v_cvt_pk_bf16_f32 v27, v30, v31
	global_store_dwordx4 v[32:33], v[24:27], off
	v_cvt_pk_bf16_f32 v8, v20, v21
	v_cvt_pk_bf16_f32 v9, v22, v23
	v_cvt_pk_bf16_f32 v10, v12, v13
	v_cvt_pk_bf16_f32 v11, v14, v15
	global_store_dwordx4 v[16:17], v[8:11], off
	v_cvt_pk_bf16_f32 v4, v4, v5
	v_cvt_pk_bf16_f32 v5, v6, v7
	v_cvt_pk_bf16_f32 v6, v0, v1
	v_cvt_pk_bf16_f32 v7, v2, v3
	global_store_dwordx4 v[16:17], v[4:7], off offset:256
	s_cbranch_vccz .LBB0_483
	s_waitcnt vmcnt(0)
	s_cmpk_gt_u32 s34, 0xff
	s_cbranch_scc1 .LBB0_498
	s_barrier
